# final LN v2: next iteration rows prefetched into spare registers, wait leaves the 16 stores in flight; plus previous edits
# baseline (speedup 1.0000x reference)
; template <class T> __device__ __forceinline__ T* lnd(T* p) { asm volatile("" : "+s"(p)); return p; }
; __device__ __forceinline__ int lnd_tid() { int t = threadIdx.x; asm volatile("" : "+v"(t)); return t; }
; #define GAS __attribute__((address_space(1)))
; __device__ void ln_final_phase(const h16* z0, const float* g0, const float* b0, float* out0) {
;     const GAS h16* z = (const GAS h16*)lnd(z0); const float* g = lnd(g0); const float* b = lnd(b0); float* out = lnd(out0);
;     const int tidl = lnd_tid(), lane = tidl & 63, gw = blockIdx.x * 8 + (tidl >> 6), nw = gridDim.x * 8;
;     for (int row0 = gw; row0 < NT; row0 += 2 * nw) {
;         f16x8 hv[2][4];
; #pragma unroll
;         for (int r = 0; r < 2; ++r)
; #pragma unroll
;             for (int i = 0; i < 4; ++i) hv[r][i] = *(const GAS f16x8*)(z + (size_t)(row0 + r * nw) * DM + 8 * (lane + 64 * i));
.LBB0_805:
	v_readlane_b32 s4, v253, 0
	s_add_u32 s0, s68, 0xcac4000
	v_readlane_b32 s14, v253, 10
	v_readlane_b32 s15, v253, 11
	v_readlane_b32 s18, v253, 14
	v_readlane_b32 s19, v253, 15
	s_addc_u32 s1, s69, 0
	s_mov_b64 s[14:15], s[18:19]
	s_add_u32 s2, s14, 0x6000
	s_addc_u32 s3, s15, 0
	v_readlane_b32 s5, v253, 1
	s_add_u32 s4, s48, 0x6000
	v_readlane_b32 s6, v253, 2
	s_addc_u32 s5, s49, 0
	v_readlane_b32 s6, v253, 27
	v_ashrrev_i32_e32 v0, 6, v252
	v_readlane_b32 s7, v253, 3
	v_add_u32_e32 v36, s6, v0
	s_movk_i32 s6, 0x4000
	v_cmp_gt_i32_e32 vcc, s6, v36
	v_readlane_b32 s8, v253, 4
	v_readlane_b32 s9, v253, 5
	v_readlane_b32 s10, v253, 6
	v_readlane_b32 s11, v253, 7
	v_readlane_b32 s12, v253, 8
	v_readlane_b32 s13, v253, 9
	v_readlane_b32 s16, v253, 12
	v_readlane_b32 s17, v253, 13
	s_and_saveexec_b64 s[6:7], vcc
	s_cbranch_execz .LBB0_808
	v_and_b32_e32 v1, 64, v221
	v_add_u32_e32 v1, 64, v1
	v_xor_b32_e32 v3, 32, v221
	v_cmp_lt_i32_e32 vcc, v3, v1
	v_lshlrev_b32_e32 v0, 3, v252
	v_and_b32_e32 v0, 0x1f8, v0
	v_cndmask_b32_e32 v3, v221, v3, vcc
	v_lshlrev_b32_e32 v33, 2, v3
	v_xor_b32_e32 v3, 16, v221
	v_cmp_lt_i32_e32 vcc, v3, v1
	v_mov_b32_e32 v13, 0
	v_or_b32_e32 v2, 0x400, v0
	v_cndmask_b32_e32 v3, v221, v3, vcc
	v_lshlrev_b32_e32 v84, 2, v3
	v_xor_b32_e32 v3, 8, v221
	v_cmp_lt_i32_e32 vcc, v3, v1
	v_lshlrev_b32_e32 v12, 2, v0
	v_or_b32_e32 v4, 0x600, v0
	v_cndmask_b32_e32 v3, v221, v3, vcc
	v_lshlrev_b32_e32 v85, 2, v3
	v_xor_b32_e32 v3, 4, v221
	v_cmp_lt_i32_e32 vcc, v3, v1
	v_lshl_add_u64 v[14:15], s[2:3], 0, v[12:13]
	v_lshl_add_u64 v[16:17], s[4:5], 0, v[12:13]
	v_cndmask_b32_e32 v3, v221, v3, vcc
	v_lshlrev_b32_e32 v86, 2, v3
	v_xor_b32_e32 v3, 2, v221
	v_cmp_lt_i32_e32 vcc, v3, v1
	v_lshlrev_b32_e32 v12, 2, v2
	v_lshl_add_u64 v[18:19], s[2:3], 0, v[12:13]
	v_cndmask_b32_e32 v3, v221, v3, vcc
	v_lshlrev_b32_e32 v87, 2, v3
	v_xor_b32_e32 v3, 1, v221
	v_cmp_lt_i32_e32 vcc, v3, v1
	v_lshl_add_u64 v[20:21], s[4:5], 0, v[12:13]
	v_lshlrev_b32_e32 v12, 2, v4
	v_cndmask_b32_e32 v1, v221, v3, vcc
	v_lshl_add_u64 v[22:23], s[2:3], 0, v[12:13]
	v_lshl_add_u64 v[24:25], s[4:5], 0, v[12:13]
	v_lshlrev_b32_e32 v12, 1, v0
	s_lshl_b32 s6, s70, 3
	v_lshlrev_b32_e32 v88, 2, v1
	v_lshl_add_u64 v[26:27], s[0:1], 0, v[12:13]
	s_mov_b64 s[0:1], 0
	v_lshlrev_b32_e32 v12, 2, v0
	v_lshlrev_b32_e32 v28, 2, v2
	v_mov_b32_e32 v29, v13
	s_mov_b32 s2, 0x3a000000
	v_lshlrev_b32_e32 v30, 2, v4
	v_mov_b32_e32 v31, v13
	v_mov_b32_e32 v32, 0x3727c5ac
	s_mov_b32 s3, 0x800000
	s_movk_i32 s4, 0x3fff
	global_load_dwordx4 v[150:153], v[14:15], off
	global_load_dwordx4 v[154:157], v[14:15], off offset:16
	global_load_dwordx4 v[158:161], v[14:15], off offset:2048
	global_load_dwordx4 v[162:165], v[14:15], off offset:2064
	global_load_dwordx4 v[166:169], v[18:19], off
	global_load_dwordx4 v[170:173], v[18:19], off offset:16
	global_load_dwordx4 v[174:177], v[22:23], off
	global_load_dwordx4 v[178:181], v[22:23], off offset:16
	global_load_dwordx4 v[182:185], v[16:17], off
	global_load_dwordx4 v[186:189], v[16:17], off offset:16
	global_load_dwordx4 v[190:193], v[16:17], off offset:2048
	global_load_dwordx4 v[194:197], v[16:17], off offset:2064
	global_load_dwordx4 v[198:201], v[20:21], off
	global_load_dwordx4 v[202:205], v[20:21], off offset:16
	global_load_dwordx4 v[206:209], v[24:25], off
	global_load_dwordx4 v[210:213], v[24:25], off offset:16
	v_mov_b32_e32 v218, v36
	v_ashrrev_i32_e32 v219, 31, v36
	v_lshlrev_b64 v[218:219], 12, v[218:219]
	v_lshl_add_u64 v[218:219], v[26:27], 0, v[218:219]
	global_load_dwordx4 v[214:217], v[218:219], off
	global_load_dwordx4 v[222:225], v[218:219], off offset:1024
	global_load_dwordx4 v[226:229], v[218:219], off offset:2048
	global_load_dwordx4 v[230:233], v[218:219], off offset:3072
	v_add_u32_e32 v250, s6, v36
	v_ashrrev_i32_e32 v251, 31, v250
	v_lshlrev_b64 v[250:251], 12, v[250:251]
	v_lshl_add_u64 v[250:251], v[26:27], 0, v[250:251]
	global_load_dwordx4 v[234:237], v[250:251], off
	global_load_dwordx4 v[238:241], v[250:251], off offset:1024
	global_load_dwordx4 v[242:245], v[250:251], off offset:2048
	global_load_dwordx4 v[246:249], v[250:251], off offset:3072
	s_waitcnt vmcnt(0)
.LBB0_807:
	s_waitcnt vmcnt(16)
	v_mov_b32_e32 v44, v214
	v_mov_b32_e32 v45, v215
	v_mov_b32_e32 v46, v216
	v_mov_b32_e32 v47, v217
	v_mov_b32_e32 v52, v222
	v_mov_b32_e32 v53, v223
	v_mov_b32_e32 v54, v224
	v_mov_b32_e32 v55, v225
	v_mov_b32_e32 v60, v226
	v_mov_b32_e32 v61, v227
	v_mov_b32_e32 v62, v228
	v_mov_b32_e32 v63, v229
	v_mov_b32_e32 v66, v230
	v_mov_b32_e32 v67, v231
	v_mov_b32_e32 v68, v232
	v_mov_b32_e32 v69, v233
	v_mov_b32_e32 v70, v234
	v_mov_b32_e32 v71, v235
	v_mov_b32_e32 v72, v236
	v_mov_b32_e32 v73, v237
	v_mov_b32_e32 v74, v238
	v_mov_b32_e32 v75, v239
	v_mov_b32_e32 v76, v240
	v_mov_b32_e32 v77, v241
	v_mov_b32_e32 v78, v242
	v_mov_b32_e32 v79, v243
	v_mov_b32_e32 v80, v244
	v_mov_b32_e32 v81, v245
	v_mov_b32_e32 v8, v246
	v_mov_b32_e32 v9, v247
	v_mov_b32_e32 v10, v248
	v_mov_b32_e32 v11, v249
	v_add_u32_e32 v34, s6, v36
	v_add_u32_e32 v218, s6, v34
	v_ashrrev_i32_e32 v219, 31, v218
	v_add_u32_e32 v250, s6, v218
	v_lshlrev_b64 v[218:219], 12, v[218:219]
	v_lshl_add_u64 v[218:219], v[26:27], 0, v[218:219]
	global_load_dwordx4 v[214:217], v[218:219], off
	global_load_dwordx4 v[222:225], v[218:219], off offset:1024
	global_load_dwordx4 v[226:229], v[218:219], off offset:2048
	global_load_dwordx4 v[230:233], v[218:219], off offset:3072
	v_ashrrev_i32_e32 v251, 31, v250
	v_lshlrev_b64 v[250:251], 12, v[250:251]
	v_lshl_add_u64 v[250:251], v[26:27], 0, v[250:251]
	global_load_dwordx4 v[234:237], v[250:251], off
; #define GAS __attribute__((address_space(1)))
; __device__ void ln_final_phase(const h16* z0, const float* g0, const float* b0, float* out0) {
;     ...
;             for (int i = 0; i < 4; ++i) hv[r][i] = *(const GAS f16x8*)(z + (size_t)(row0 + r * nw) * DM + 8 * (lane + 64 * i));
; #pragma unroll
;         for (int r = 0; r < 2; ++r) {
;             const int row = row0 + r * nw; float s = 0.f;
; #pragma unroll
;             for (int i = 0; i < 4; ++i)
; #pragma unroll
;                 for (int j = 0; j < 8; ++j) s += (float)hv[r][i][j];
	global_load_dwordx4 v[238:241], v[250:251], off offset:1024
	global_load_dwordx4 v[242:245], v[250:251], off offset:2048
	global_load_dwordx4 v[246:249], v[250:251], off offset:3072
	v_ashrrev_i32_e32 v35, 31, v34
	v_ashrrev_i32_e32 v37, 31, v36
	v_lshlrev_b64 v[36:37], 13, v[36:37]
	v_lshl_add_u64 v[36:37], s[50:51], 0, v[36:37]
	v_mov_b32_e32 v0, v154
	v_mov_b32_e32 v1, v155
	v_mov_b32_e32 v2, v156
	v_mov_b32_e32 v3, v157
	v_mov_b32_e32 v4, v150
	v_mov_b32_e32 v5, v151
	v_mov_b32_e32 v6, v152
	v_mov_b32_e32 v7, v153
	v_mov_b32_e32 v90, v186
	v_mov_b32_e32 v91, v187
	v_mov_b32_e32 v92, v188
	v_mov_b32_e32 v93, v189
	v_mov_b32_e32 v94, v182
	v_mov_b32_e32 v95, v183
	v_mov_b32_e32 v96, v184
	v_mov_b32_e32 v97, v185
	v_cvt_f32_f16_e32 v42, v44
	v_cvt_f32_f16_sdwa v43, v44 dst_sel:DWORD dst_unused:UNUSED_PAD src0_sel:WORD_1
	v_cvt_f32_f16_e32 v44, v45
	v_cvt_f32_f16_sdwa v45, v45 dst_sel:DWORD dst_unused:UNUSED_PAD src0_sel:WORD_1
	v_cvt_f32_f16_e32 v38, v46
	v_cvt_f32_f16_e32 v122, v10
	v_cvt_f32_f16_sdwa v123, v10 dst_sel:DWORD dst_unused:UNUSED_PAD src0_sel:WORD_1
	v_cvt_f32_f16_e32 v82, v11
	v_cvt_f32_f16_sdwa v83, v11 dst_sel:DWORD dst_unused:UNUSED_PAD src0_sel:WORD_1
	v_cvt_f32_f16_e32 v10, v8
	v_cvt_f32_f16_sdwa v11, v8 dst_sel:DWORD dst_unused:UNUSED_PAD src0_sel:WORD_1
	v_add_f32_e32 v8, 0, v42
	v_cvt_f32_f16_sdwa v39, v46 dst_sel:DWORD dst_unused:UNUSED_PAD src0_sel:WORD_1
	v_add_f32_e32 v8, v8, v43
	v_cvt_f32_f16_e32 v40, v47
	v_add_f32_e32 v8, v8, v44
	v_cvt_f32_f16_sdwa v41, v47 dst_sel:DWORD dst_unused:UNUSED_PAD src0_sel:WORD_1
	v_add_f32_e32 v8, v8, v45
	v_cvt_f32_f16_e32 v50, v52
	v_add_f32_e32 v8, v8, v38
	v_cvt_f32_f16_sdwa v51, v52 dst_sel:DWORD dst_unused:UNUSED_PAD src0_sel:WORD_1
	v_add_f32_e32 v8, v8, v39
	v_cvt_f32_f16_e32 v52, v53
	v_add_f32_e32 v8, v8, v40
	v_cvt_f32_f16_sdwa v53, v53 dst_sel:DWORD dst_unused:UNUSED_PAD src0_sel:WORD_1
	v_add_f32_e32 v8, v8, v41
	v_cvt_f32_f16_e32 v46, v54
	v_add_f32_e32 v8, v8, v50
	v_cvt_f32_f16_sdwa v47, v54 dst_sel:DWORD dst_unused:UNUSED_PAD src0_sel:WORD_1
	v_add_f32_e32 v8, v8, v51
	v_cvt_f32_f16_e32 v48, v55
	v_add_f32_e32 v8, v8, v52
	v_cvt_f32_f16_sdwa v49, v55 dst_sel:DWORD dst_unused:UNUSED_PAD src0_sel:WORD_1
	v_add_f32_e32 v8, v8, v53
	v_cvt_f32_f16_e32 v58, v60
	v_add_f32_e32 v8, v8, v46
	v_cvt_f32_f16_sdwa v59, v60 dst_sel:DWORD dst_unused:UNUSED_PAD src0_sel:WORD_1
	v_add_f32_e32 v8, v8, v47
	v_cvt_f32_f16_e32 v60, v61
	v_add_f32_e32 v8, v8, v48
	v_cvt_f32_f16_sdwa v61, v61 dst_sel:DWORD dst_unused:UNUSED_PAD src0_sel:WORD_1
	v_add_f32_e32 v8, v8, v49
	v_cvt_f32_f16_e32 v54, v62
	v_add_f32_e32 v8, v8, v58
	v_cvt_f32_f16_sdwa v55, v62 dst_sel:DWORD dst_unused:UNUSED_PAD src0_sel:WORD_1
	v_add_f32_e32 v8, v8, v59
	v_cvt_f32_f16_e32 v56, v63
	v_add_f32_e32 v8, v8, v60
	v_cvt_f32_f16_sdwa v57, v63 dst_sel:DWORD dst_unused:UNUSED_PAD src0_sel:WORD_1
	v_add_f32_e32 v8, v8, v61
	v_cvt_f32_f16_e32 v62, v68
	v_cvt_f32_f16_sdwa v63, v68 dst_sel:DWORD dst_unused:UNUSED_PAD src0_sel:WORD_1
	v_cvt_f32_f16_e32 v68, v66
	v_add_f32_e32 v8, v8, v54
	v_cvt_f32_f16_e32 v64, v69
	v_cvt_f32_f16_sdwa v65, v69 dst_sel:DWORD dst_unused:UNUSED_PAD src0_sel:WORD_1
	v_cvt_f32_f16_sdwa v69, v66 dst_sel:DWORD dst_unused:UNUSED_PAD src0_sel:WORD_1
	v_add_f32_e32 v8, v8, v55
	v_cvt_f32_f16_e32 v66, v67
	v_cvt_f32_f16_e32 v102, v70
	v_add_f32_e32 v8, v8, v56
	v_cvt_f32_f16_sdwa v67, v67 dst_sel:DWORD dst_unused:UNUSED_PAD src0_sel:WORD_1
	v_cvt_f32_f16_sdwa v103, v70 dst_sel:DWORD dst_unused:UNUSED_PAD src0_sel:WORD_1
	v_add_f32_e32 v8, v8, v57
	v_cvt_f32_f16_e32 v104, v71
	v_add_f32_e32 v8, v8, v68
	v_cvt_f32_f16_sdwa v105, v71 dst_sel:DWORD dst_unused:UNUSED_PAD src0_sel:WORD_1
	v_add_f32_e32 v8, v8, v69
	v_cvt_f32_f16_e32 v98, v72
	v_add_f32_e32 v70, 0, v102
	v_add_f32_e32 v8, v8, v66
	v_cvt_f32_f16_sdwa v99, v72 dst_sel:DWORD dst_unused:UNUSED_PAD src0_sel:WORD_1
	v_add_f32_e32 v70, v70, v103
	v_add_f32_e32 v8, v8, v67
	v_cvt_f32_f16_e32 v100, v73
	v_add_f32_e32 v70, v70, v104
	v_add_f32_e32 v8, v8, v62
	v_cvt_f32_f16_sdwa v101, v73 dst_sel:DWORD dst_unused:UNUSED_PAD src0_sel:WORD_1
	v_add_f32_e32 v70, v70, v105
	v_add_f32_e32 v8, v8, v63
	v_cvt_f32_f16_e32 v110, v74
	v_add_f32_e32 v70, v70, v98
	v_add_f32_e32 v8, v8, v64
	v_cvt_f32_f16_sdwa v111, v74 dst_sel:DWORD dst_unused:UNUSED_PAD src0_sel:WORD_1
	v_add_f32_e32 v70, v70, v99
	v_add_f32_e32 v8, v8, v65
	v_cvt_f32_f16_e32 v112, v75
	v_add_f32_e32 v70, v70, v100
	ds_bpermute_b32 v71, v33, v8
	v_cvt_f32_f16_sdwa v113, v75 dst_sel:DWORD dst_unused:UNUSED_PAD src0_sel:WORD_1
	v_add_f32_e32 v70, v70, v101
	v_cvt_f32_f16_e32 v106, v76
	v_add_f32_e32 v70, v70, v110
	v_cvt_f32_f16_sdwa v107, v76 dst_sel:DWORD dst_unused:UNUSED_PAD src0_sel:WORD_1
	v_add_f32_e32 v70, v70, v111
	v_cvt_f32_f16_e32 v108, v77
	v_add_f32_e32 v70, v70, v112
	v_cvt_f32_f16_sdwa v109, v77 dst_sel:DWORD dst_unused:UNUSED_PAD src0_sel:WORD_1
	v_add_f32_e32 v70, v70, v113
	s_waitcnt lgkmcnt(0)
	v_add_f32_e32 v8, v8, v71
	v_cvt_f32_f16_e32 v118, v78
	ds_bpermute_b32 v71, v84, v8
	v_add_f32_e32 v70, v70, v106
	v_cvt_f32_f16_sdwa v119, v78 dst_sel:DWORD dst_unused:UNUSED_PAD src0_sel:WORD_1
	v_add_f32_e32 v70, v70, v107
	v_cvt_f32_f16_e32 v120, v79
	v_add_f32_e32 v70, v70, v108
	v_cvt_f32_f16_sdwa v121, v79 dst_sel:DWORD dst_unused:UNUSED_PAD src0_sel:WORD_1
	v_add_f32_e32 v70, v70, v109
	v_cvt_f32_f16_e32 v114, v80
	v_add_f32_e32 v70, v70, v118
	v_cvt_f32_f16_sdwa v115, v80 dst_sel:DWORD dst_unused:UNUSED_PAD src0_sel:WORD_1
	s_waitcnt lgkmcnt(0)
; __device__ void ln_final_phase(const h16* z0, const float* g0, const float* b0, float* out0) {
;     ...
;                 for (int j = 0; j < 8; ++j) s += (float)hv[r][i][j];
; #pragma unroll
;             for (int o = 32; o >= 1; o >>= 1) s += __shfl_xor(s, o);
;             const float mean = s * (1.0f / DM); float q = 0.f;
; #pragma unroll
;             for (int i = 0; i < 4; ++i)
; #pragma unroll
;                 for (int j = 0; j < 8; ++j) { const float d = (float)hv[r][i][j] - mean; q += d * d; }
; #pragma unroll
;             for (int o = 32; o >= 1; o >>= 1) q += __shfl_xor(q, o);
	v_add_f32_e32 v8, v8, v71
	v_add_f32_e32 v70, v70, v119
	v_cvt_f32_f16_e32 v116, v81
	ds_bpermute_b32 v71, v85, v8
	v_add_f32_e32 v70, v70, v120
	v_cvt_f32_f16_sdwa v117, v81 dst_sel:DWORD dst_unused:UNUSED_PAD src0_sel:WORD_1
	v_add_f32_e32 v70, v70, v121
	v_add_f32_e32 v70, v70, v114
	v_add_f32_e32 v70, v70, v115
	v_add_f32_e32 v70, v70, v116
	v_cvt_f32_f16_e32 v124, v9
	s_waitcnt lgkmcnt(0)
	v_add_f32_e32 v8, v8, v71
	v_add_f32_e32 v70, v70, v117
	v_cvt_f32_f16_sdwa v125, v9 dst_sel:DWORD dst_unused:UNUSED_PAD src0_sel:WORD_1
	ds_bpermute_b32 v71, v86, v8
	v_add_f32_e32 v9, v70, v10
	v_add_f32_e32 v9, v9, v11
	v_add_f32_e32 v9, v9, v124
	v_add_f32_e32 v9, v9, v125
	v_add_f32_e32 v9, v9, v122
	s_waitcnt lgkmcnt(0)
	v_add_f32_e32 v8, v8, v71
	v_add_f32_e32 v9, v9, v123
	ds_bpermute_b32 v71, v87, v8
	v_add_f32_e32 v9, v9, v82
	v_add_f32_e32 v9, v9, v83
	ds_bpermute_b32 v70, v33, v9
	s_waitcnt lgkmcnt(1)
	v_add_f32_e32 v8, v8, v71
	ds_bpermute_b32 v71, v88, v8
	s_waitcnt lgkmcnt(1)
	v_add_f32_e32 v9, v9, v70
	ds_bpermute_b32 v70, v84, v9
	s_waitcnt lgkmcnt(1)
	v_add_f32_e32 v8, v8, v71
	v_mul_f32_e32 v8, 0x3a000000, v8
	v_pk_add_f32 v[126:127], v[42:43], v[8:9] op_sel_hi:[1,0] neg_lo:[0,1] neg_hi:[0,1]
	v_pk_add_f32 v[128:129], v[44:45], v[8:9] op_sel_hi:[1,0] neg_lo:[0,1] neg_hi:[0,1]
	s_waitcnt lgkmcnt(0)
	v_add_f32_e32 v9, v9, v70
	ds_bpermute_b32 v42, v85, v9
	v_pk_add_f32 v[130:131], v[38:39], v[8:9] op_sel_hi:[1,0] neg_lo:[0,1] neg_hi:[0,1]
	v_pk_add_f32 v[132:133], v[40:41], v[8:9] op_sel_hi:[1,0] neg_lo:[0,1] neg_hi:[0,1]
	v_pk_add_f32 v[134:135], v[50:51], v[8:9] op_sel_hi:[1,0] neg_lo:[0,1] neg_hi:[0,1]
	v_pk_add_f32 v[136:137], v[52:53], v[8:9] op_sel_hi:[1,0] neg_lo:[0,1] neg_hi:[0,1]
	s_waitcnt lgkmcnt(0)
	v_add_f32_e32 v9, v9, v42
	ds_bpermute_b32 v38, v86, v9
	v_pk_add_f32 v[138:139], v[46:47], v[8:9] op_sel_hi:[1,0] neg_lo:[0,1] neg_hi:[0,1]
	v_pk_add_f32 v[140:141], v[48:49], v[8:9] op_sel_hi:[1,0] neg_lo:[0,1] neg_hi:[0,1]
	v_pk_add_f32 v[78:79], v[58:59], v[8:9] op_sel_hi:[1,0] neg_lo:[0,1] neg_hi:[0,1]
	v_pk_add_f32 v[80:81], v[60:61], v[8:9] op_sel_hi:[1,0] neg_lo:[0,1] neg_hi:[0,1]
	s_waitcnt lgkmcnt(0)
	v_add_f32_e32 v9, v9, v38
	ds_bpermute_b32 v38, v87, v9
	v_pk_add_f32 v[74:75], v[54:55], v[8:9] op_sel_hi:[1,0] neg_lo:[0,1] neg_hi:[0,1]
	v_pk_add_f32 v[76:77], v[56:57], v[8:9] op_sel_hi:[1,0] neg_lo:[0,1] neg_hi:[0,1]
	v_pk_add_f32 v[70:71], v[68:69], v[8:9] op_sel_hi:[1,0] neg_lo:[0,1] neg_hi:[0,1]
	v_pk_add_f32 v[72:73], v[66:67], v[8:9] op_sel_hi:[1,0] neg_lo:[0,1] neg_hi:[0,1]
	s_waitcnt lgkmcnt(0)
	v_add_f32_e32 v9, v9, v38
	ds_bpermute_b32 v38, v88, v9
	v_pk_add_f32 v[66:67], v[62:63], v[8:9] op_sel_hi:[1,0] neg_lo:[0,1] neg_hi:[0,1]
	v_pk_add_f32 v[68:69], v[64:65], v[8:9] op_sel_hi:[1,0] neg_lo:[0,1] neg_hi:[0,1]
	v_mov_b32_e32 v39, v127
	v_pk_mul_f32 v[142:143], v[66:67], v[66:67]
	s_waitcnt lgkmcnt(0)
	v_add_f32_e32 v8, v9, v38
	v_mul_f32_e32 v46, 0x3a000000, v8
	v_pk_add_f32 v[52:53], v[102:103], v[46:47] op_sel_hi:[1,0] neg_lo:[0,1] neg_hi:[0,1]
	v_pk_add_f32 v[56:57], v[104:105], v[46:47] op_sel_hi:[1,0] neg_lo:[0,1] neg_hi:[0,1]
	v_mov_b32_e32 v38, v53
	v_mov_b32_e32 v8, v52
	v_mov_b32_e32 v9, v126
	v_pk_mul_f32 v[38:39], v[38:39], v[38:39]
	v_pk_add_f32 v[42:43], v[98:99], v[46:47] op_sel_hi:[1,0] neg_lo:[0,1] neg_hi:[0,1]
	v_pk_fma_f32 v[8:9], v[8:9], v[8:9], v[38:39]
	v_mov_b32_e32 v38, v56
	v_mov_b32_e32 v39, v128
	v_pk_fma_f32 v[8:9], v[38:39], v[38:39], v[8:9]
	v_mov_b32_e32 v38, v57
	v_mov_b32_e32 v39, v129
	v_pk_fma_f32 v[8:9], v[38:39], v[38:39], v[8:9]
	v_mov_b32_e32 v38, v42
	v_mov_b32_e32 v39, v130
	v_pk_add_f32 v[48:49], v[100:101], v[46:47] op_sel_hi:[1,0] neg_lo:[0,1] neg_hi:[0,1]
	v_pk_fma_f32 v[8:9], v[38:39], v[38:39], v[8:9]
	v_mov_b32_e32 v38, v43
	v_mov_b32_e32 v39, v131
	v_pk_fma_f32 v[8:9], v[38:39], v[38:39], v[8:9]
	v_mov_b32_e32 v38, v48
	v_mov_b32_e32 v39, v132
	v_pk_fma_f32 v[8:9], v[38:39], v[38:39], v[8:9]
	v_mov_b32_e32 v38, v49
	v_mov_b32_e32 v39, v133
	v_pk_add_f32 v[54:55], v[110:111], v[46:47] op_sel_hi:[1,0] neg_lo:[0,1] neg_hi:[0,1]
	v_pk_fma_f32 v[8:9], v[38:39], v[38:39], v[8:9]
	v_mov_b32_e32 v38, v54
	v_mov_b32_e32 v39, v134
	v_pk_add_f32 v[58:59], v[112:113], v[46:47] op_sel_hi:[1,0] neg_lo:[0,1] neg_hi:[0,1]
	v_pk_fma_f32 v[8:9], v[38:39], v[38:39], v[8:9]
	v_mov_b32_e32 v38, v55
	v_mov_b32_e32 v39, v135
	v_pk_fma_f32 v[8:9], v[38:39], v[38:39], v[8:9]
	v_mov_b32_e32 v38, v58
	v_mov_b32_e32 v39, v136
	v_pk_add_f32 v[44:45], v[106:107], v[46:47] op_sel_hi:[1,0] neg_lo:[0,1] neg_hi:[0,1]
	v_pk_fma_f32 v[8:9], v[38:39], v[38:39], v[8:9]
	v_mov_b32_e32 v38, v59
	v_mov_b32_e32 v39, v137
	v_pk_fma_f32 v[8:9], v[38:39], v[38:39], v[8:9]
	v_mov_b32_e32 v38, v44
	v_mov_b32_e32 v39, v138
	v_pk_add_f32 v[50:51], v[108:109], v[46:47] op_sel_hi:[1,0] neg_lo:[0,1] neg_hi:[0,1]
	v_pk_fma_f32 v[8:9], v[38:39], v[38:39], v[8:9]
	v_mov_b32_e32 v38, v45
	v_mov_b32_e32 v39, v139
	v_pk_fma_f32 v[8:9], v[38:39], v[38:39], v[8:9]
	v_mov_b32_e32 v38, v50
	v_mov_b32_e32 v39, v140
	v_pk_add_f32 v[40:41], v[118:119], v[46:47] op_sel_hi:[1,0] neg_lo:[0,1] neg_hi:[0,1]
	v_pk_fma_f32 v[8:9], v[38:39], v[38:39], v[8:9]
	v_mov_b32_e32 v38, v51
	v_mov_b32_e32 v39, v141
	v_pk_fma_f32 v[8:9], v[38:39], v[38:39], v[8:9]
	v_mov_b32_e32 v38, v40
	v_mov_b32_e32 v39, v78
	v_pk_fma_f32 v[8:9], v[38:39], v[38:39], v[8:9]
	v_mov_b32_e32 v38, v41
	v_mov_b32_e32 v39, v79
	v_pk_add_f32 v[64:65], v[120:121], v[46:47] op_sel_hi:[1,0] neg_lo:[0,1] neg_hi:[0,1]
	v_pk_fma_f32 v[98:99], v[38:39], v[38:39], v[8:9]
	v_mov_b32_e32 v100, v64
	v_mov_b32_e32 v101, v80
; __device__ void ln_final_phase(const h16* z0, const float* g0, const float* b0, float* out0) {
;     ...
;             for (int i = 0; i < 4; ++i)
; #pragma unroll
;                 for (int j = 0; j < 8; ++j) { const float d = (float)hv[r][i][j] - mean; q += d * d; }
; #pragma unroll
;             for (int o = 32; o >= 1; o >>= 1) q += __shfl_xor(q, o);
;             const float rstd = rsqrtf(q * (1.0f / DM) + LN_EPS);
; #pragma unroll
;             for (int i = 0; i < 4; ++i) { const int col = 8 * (lane + 64 * i);
;                 const f32x4 g0v = ldg4(g + col), g1v = ldg4(g + col + 4), b0v = ldg4(b + col), b1v = ldg4(b + col + 4);
;                 f32x4 y0, y1;
; #pragma unroll
;                 for (int j = 0; j < 4; ++j) { y0[j] = ((float)hv[r][i][j] - mean) * rstd * g0v[j] + b0v[j]; y1[j] = ((float)hv[r][i][4 + j] - mean) * rstd * g1v[j] + b1v[j]; }
;                 stg4(out + (size_t)row * DM + col, y0); stg4(out + (size_t)row * DM + col + 4, y1); }
	v_pk_add_f32 v[60:61], v[114:115], v[46:47] op_sel_hi:[1,0] neg_lo:[0,1] neg_hi:[0,1]
	v_pk_fma_f32 v[98:99], v[100:101], v[100:101], v[98:99]
	v_mov_b32_e32 v100, v65
	v_mov_b32_e32 v101, v81
	v_pk_fma_f32 v[98:99], v[100:101], v[100:101], v[98:99]
	v_mov_b32_e32 v100, v60
	v_mov_b32_e32 v101, v74
	v_pk_add_f32 v[62:63], v[116:117], v[46:47] op_sel_hi:[1,0] neg_lo:[0,1] neg_hi:[0,1]
	v_pk_fma_f32 v[98:99], v[100:101], v[100:101], v[98:99]
	v_mov_b32_e32 v100, v61
	v_mov_b32_e32 v101, v75
	v_pk_fma_f32 v[98:99], v[100:101], v[100:101], v[98:99]
	v_mov_b32_e32 v100, v62
	v_mov_b32_e32 v101, v76
	v_pk_add_f32 v[8:9], v[10:11], v[46:47] op_sel_hi:[1,0] neg_lo:[0,1] neg_hi:[0,1]
	v_pk_fma_f32 v[98:99], v[100:101], v[100:101], v[98:99]
	v_mov_b32_e32 v100, v63
	v_mov_b32_e32 v101, v77
	v_pk_fma_f32 v[98:99], v[100:101], v[100:101], v[98:99]
	v_mov_b32_e32 v100, v8
	v_mov_b32_e32 v101, v70
	v_pk_add_f32 v[38:39], v[124:125], v[46:47] op_sel_hi:[1,0] neg_lo:[0,1] neg_hi:[0,1]
	v_pk_fma_f32 v[98:99], v[100:101], v[100:101], v[98:99]
	v_mov_b32_e32 v100, v9
	v_mov_b32_e32 v101, v71
	v_pk_add_f32 v[10:11], v[122:123], v[46:47] op_sel_hi:[1,0] neg_lo:[0,1] neg_hi:[0,1]
	v_pk_fma_f32 v[98:99], v[100:101], v[100:101], v[98:99]
	v_mov_b32_e32 v100, v38
	v_mov_b32_e32 v101, v72
	v_pk_mul_f32 v[102:103], v[10:11], v[10:11]
	v_pk_fma_f32 v[98:99], v[100:101], v[100:101], v[98:99]
	v_mov_b32_e32 v100, v39
	v_mov_b32_e32 v101, v73
	v_pk_fma_f32 v[98:99], v[100:101], v[100:101], v[98:99]
	v_mov_b32_e32 v100, v102
	v_mov_b32_e32 v101, v142
	v_pk_add_f32 v[46:47], v[82:83], v[46:47] op_sel_hi:[1,0] neg_lo:[0,1] neg_hi:[0,1]
	v_pk_mul_f32 v[144:145], v[68:69], v[68:69]
	v_pk_add_f32 v[98:99], v[100:101], v[98:99]
	v_pk_mul_f32 v[82:83], v[46:47], v[46:47]
	v_mov_b32_e32 v142, v103
	v_pk_add_f32 v[98:99], v[142:143], v[98:99]
	v_mov_b32_e32 v100, v82
	v_mov_b32_e32 v101, v144
	v_pk_add_f32 v[98:99], v[100:101], v[98:99]
	v_mov_b32_e32 v144, v83
	v_pk_add_f32 v[82:83], v[144:145], v[98:99]
	ds_bpermute_b32 v99, v33, v83
	ds_bpermute_b32 v98, v33, v82
	s_waitcnt lgkmcnt(0)
	v_pk_add_f32 v[82:83], v[82:83], v[98:99]
	ds_bpermute_b32 v99, v84, v83
	ds_bpermute_b32 v98, v84, v82
	s_waitcnt lgkmcnt(0)
	v_pk_add_f32 v[82:83], v[82:83], v[98:99]
	ds_bpermute_b32 v99, v85, v83
	ds_bpermute_b32 v98, v85, v82
	s_waitcnt lgkmcnt(0)
	v_pk_add_f32 v[82:83], v[82:83], v[98:99]
	ds_bpermute_b32 v99, v86, v83
	ds_bpermute_b32 v98, v86, v82
	s_waitcnt lgkmcnt(0)
	v_pk_add_f32 v[82:83], v[82:83], v[98:99]
	ds_bpermute_b32 v99, v87, v83
	ds_bpermute_b32 v98, v87, v82
	s_waitcnt lgkmcnt(0)
	v_pk_add_f32 v[82:83], v[82:83], v[98:99]
	ds_bpermute_b32 v99, v88, v83
	ds_bpermute_b32 v98, v88, v82
	s_waitcnt lgkmcnt(0)
	v_pk_add_f32 v[82:83], v[82:83], v[98:99]
	s_nop 0
	v_pk_fma_f32 v[82:83], v[82:83], s[2:3], v[32:33] op_sel_hi:[1,0,0]
	v_lshl_add_u64 v[98:99], v[36:37], 0, v[12:13]
	v_mul_f32_e32 v89, 0x4b800000, v83
	v_cmp_gt_f32_e32 vcc, s3, v83
	s_nop 1
	v_cndmask_b32_e32 v83, v83, v89, vcc
	v_rsq_f32_e32 v83, v83
	s_nop 0
	v_mul_f32_e32 v89, 0x45800000, v83
	v_cndmask_b32_e32 v100, v83, v89, vcc
	v_pk_mul_f32 v[102:103], v[126:127], v[100:101] op_sel_hi:[1,0]
	v_pk_mul_f32 v[104:105], v[128:129], v[100:101] op_sel_hi:[1,0]
	v_pk_fma_f32 v[4:5], v[4:5], v[102:103], v[94:95]
	v_pk_fma_f32 v[6:7], v[6:7], v[104:105], v[96:97]
	v_pk_mul_f32 v[94:95], v[130:131], v[100:101] op_sel_hi:[1,0]
	v_pk_mul_f32 v[96:97], v[132:133], v[100:101] op_sel_hi:[1,0]
	v_pk_fma_f32 v[0:1], v[0:1], v[94:95], v[90:91]
	v_pk_fma_f32 v[2:3], v[2:3], v[96:97], v[92:93]
	global_store_dwordx4 v[98:99], v[4:7], off
	global_store_dwordx4 v[98:99], v[0:3], off offset:16
	s_nop 1
	v_mov_b32_e32 v0, v190
	v_mov_b32_e32 v1, v191
	v_mov_b32_e32 v2, v192
	v_mov_b32_e32 v3, v193
	s_nop 0
	v_mov_b32_e32 v4, v158
	v_mov_b32_e32 v5, v159
	v_mov_b32_e32 v6, v160
	v_mov_b32_e32 v7, v161
	v_mov_b32_e32 v90, v162
	v_mov_b32_e32 v91, v163
	v_mov_b32_e32 v92, v164
	v_mov_b32_e32 v93, v165
	v_mov_b32_e32 v94, v194
	v_mov_b32_e32 v95, v195
	v_mov_b32_e32 v96, v196
	v_mov_b32_e32 v97, v197
	v_pk_mul_f32 v[102:103], v[136:137], v[100:101] op_sel_hi:[1,0]
	v_pk_mul_f32 v[104:105], v[134:135], v[100:101] op_sel_hi:[1,0]
	v_pk_mul_f32 v[80:81], v[80:81], v[100:101] op_sel_hi:[1,0]
	v_pk_mul_f32 v[78:79], v[78:79], v[100:101] op_sel_hi:[1,0]
	v_pk_mul_f32 v[76:77], v[76:77], v[100:101] op_sel_hi:[1,0]
	v_pk_mul_f32 v[74:75], v[74:75], v[100:101] op_sel_hi:[1,0]
	v_pk_mul_f32 v[72:73], v[72:73], v[100:101] op_sel_hi:[1,0]
	v_pk_mul_f32 v[70:71], v[70:71], v[100:101] op_sel_hi:[1,0]
	v_pk_mul_f32 v[68:69], v[68:69], v[100:101] op_sel_hi:[1,0]
	v_pk_mul_f32 v[66:67], v[66:67], v[100:101] op_sel_hi:[1,0]
	v_cmp_gt_f32_e32 vcc, s3, v82
	v_pk_fma_f32 v[0:1], v[4:5], v[104:105], v[0:1]
	v_pk_fma_f32 v[2:3], v[6:7], v[102:103], v[2:3]
	v_pk_mul_f32 v[6:7], v[140:141], v[100:101] op_sel_hi:[1,0]
	v_pk_mul_f32 v[4:5], v[138:139], v[100:101] op_sel_hi:[1,0]
	v_pk_fma_f32 v[6:7], v[92:93], v[6:7], v[96:97]
	v_pk_fma_f32 v[4:5], v[90:91], v[4:5], v[94:95]
	global_store_dwordx4 v[98:99], v[0:3], off offset:2048
	global_store_dwordx4 v[98:99], v[4:7], off offset:2064
	s_nop 1
	v_mov_b32_e32 v0, v198
	v_mov_b32_e32 v1, v199
	v_mov_b32_e32 v2, v200
	v_mov_b32_e32 v3, v201
	s_nop 0
	v_mov_b32_e32 v4, v166
	v_mov_b32_e32 v5, v167
	v_mov_b32_e32 v6, v168
	v_mov_b32_e32 v7, v169
	v_mov_b32_e32 v90, v170
	v_mov_b32_e32 v91, v171
	v_mov_b32_e32 v92, v172
	v_mov_b32_e32 v93, v173
	v_mov_b32_e32 v94, v202
; __device__ void ln_final_phase(const h16* z0, const float* g0, const float* b0, float* out0) {
;     ...
;             const float rstd = rsqrtf(q * (1.0f / DM) + LN_EPS);
; #pragma unroll
;             for (int i = 0; i < 4; ++i) { const int col = 8 * (lane + 64 * i);
;                 const f32x4 g0v = ldg4(g + col), g1v = ldg4(g + col + 4), b0v = ldg4(b + col), b1v = ldg4(b + col + 4);
;                 f32x4 y0, y1;
; #pragma unroll
;                 for (int j = 0; j < 4; ++j) { y0[j] = ((float)hv[r][i][j] - mean) * rstd * g0v[j] + b0v[j]; y1[j] = ((float)hv[r][i][4 + j] - mean) * rstd * g1v[j] + b1v[j]; }
;                 stg4(out + (size_t)row * DM + col, y0); stg4(out + (size_t)row * DM + col + 4, y1); }
	v_mov_b32_e32 v95, v203
	v_mov_b32_e32 v96, v204
	v_mov_b32_e32 v97, v205
	v_lshl_add_u64 v[98:99], v[36:37], 0, v[28:29]
	v_lshl_add_u64 v[36:37], v[36:37], 0, v[30:31]
	v_pk_fma_f32 v[0:1], v[4:5], v[78:79], v[0:1]
	v_pk_fma_f32 v[2:3], v[6:7], v[80:81], v[2:3]
	v_pk_fma_f32 v[4:5], v[90:91], v[74:75], v[94:95]
	v_pk_fma_f32 v[6:7], v[92:93], v[76:77], v[96:97]
	global_store_dwordx4 v[98:99], v[0:3], off
	global_store_dwordx4 v[98:99], v[4:7], off offset:16
	s_nop 1
	v_mov_b32_e32 v0, v206
	v_mov_b32_e32 v1, v207
	v_mov_b32_e32 v2, v208
	v_mov_b32_e32 v3, v209
	s_nop 0
	v_mov_b32_e32 v4, v174
	v_mov_b32_e32 v5, v175
	v_mov_b32_e32 v6, v176
	v_mov_b32_e32 v7, v177
	v_mov_b32_e32 v74, v178
	v_mov_b32_e32 v75, v179
	v_mov_b32_e32 v76, v180
	v_mov_b32_e32 v77, v181
	v_mov_b32_e32 v78, v210
	v_mov_b32_e32 v79, v211
	v_mov_b32_e32 v80, v212
	v_mov_b32_e32 v81, v213
	v_pk_fma_f32 v[0:1], v[4:5], v[70:71], v[0:1]
	v_pk_fma_f32 v[2:3], v[6:7], v[72:73], v[2:3]
	v_pk_fma_f32 v[4:5], v[74:75], v[66:67], v[78:79]
	v_pk_fma_f32 v[6:7], v[76:77], v[68:69], v[80:81]
	global_store_dwordx4 v[36:37], v[0:3], off
	global_store_dwordx4 v[36:37], v[4:7], off offset:16
	s_nop 1
	v_mov_b32_e32 v0, v182
	v_mov_b32_e32 v1, v183
	v_mov_b32_e32 v2, v184
	v_mov_b32_e32 v3, v185
	s_nop 0
	v_mov_b32_e32 v4, v150
	v_mov_b32_e32 v5, v151
	v_mov_b32_e32 v6, v152
	v_mov_b32_e32 v7, v153
	v_mov_b32_e32 v66, v154
	v_mov_b32_e32 v67, v155
	v_mov_b32_e32 v68, v156
	v_mov_b32_e32 v69, v157
	v_mov_b32_e32 v70, v186
	v_mov_b32_e32 v71, v187
	v_mov_b32_e32 v72, v188
	v_mov_b32_e32 v73, v189
	v_mul_f32_e32 v36, 0x4b800000, v82
	v_cndmask_b32_e32 v36, v82, v36, vcc
	v_rsq_f32_e32 v76, v36
	v_lshlrev_b64 v[36:37], 13, v[34:35]
	v_lshl_add_u64 v[74:75], s[50:51], 0, v[36:37]
	v_lshl_add_u64 v[36:37], v[74:75], 0, v[12:13]
	v_mul_f32_e32 v35, 0x45800000, v76
	v_cndmask_b32_e32 v76, v76, v35, vcc
	v_pk_mul_f32 v[56:57], v[56:57], v[76:77] op_sel_hi:[1,0]
	v_pk_mul_f32 v[52:53], v[52:53], v[76:77] op_sel_hi:[1,0]
	v_pk_mul_f32 v[48:49], v[48:49], v[76:77] op_sel_hi:[1,0]
	v_pk_mul_f32 v[42:43], v[42:43], v[76:77] op_sel_hi:[1,0]
	v_pk_mul_f32 v[50:51], v[50:51], v[76:77] op_sel_hi:[1,0]
	v_pk_mul_f32 v[44:45], v[44:45], v[76:77] op_sel_hi:[1,0]
	v_pk_mul_f32 v[40:41], v[40:41], v[76:77] op_sel_hi:[1,0]
	v_pk_mul_f32 v[38:39], v[38:39], v[76:77] op_sel_hi:[1,0]
	v_pk_mul_f32 v[8:9], v[8:9], v[76:77] op_sel_hi:[1,0]
	v_pk_mul_f32 v[10:11], v[10:11], v[76:77] op_sel_hi:[1,0]
	v_pk_fma_f32 v[0:1], v[4:5], v[52:53], v[0:1]
	v_pk_fma_f32 v[2:3], v[6:7], v[56:57], v[2:3]
	v_pk_fma_f32 v[4:5], v[66:67], v[42:43], v[70:71]
	v_pk_fma_f32 v[6:7], v[68:69], v[48:49], v[72:73]
	global_store_dwordx4 v[36:37], v[0:3], off
	global_store_dwordx4 v[36:37], v[4:7], off offset:16
	s_nop 1
	v_mov_b32_e32 v0, v190
	v_mov_b32_e32 v1, v191
	v_mov_b32_e32 v2, v192
	v_mov_b32_e32 v3, v193
	s_nop 0
	v_mov_b32_e32 v4, v158
	v_mov_b32_e32 v5, v159
	v_mov_b32_e32 v6, v160
	v_mov_b32_e32 v7, v161
	v_mov_b32_e32 v66, v162
	v_mov_b32_e32 v67, v163
	v_mov_b32_e32 v68, v164
	v_mov_b32_e32 v69, v165
	v_mov_b32_e32 v70, v194
	v_mov_b32_e32 v71, v195
	v_mov_b32_e32 v72, v196
	v_mov_b32_e32 v73, v197
	v_pk_mul_f32 v[42:43], v[58:59], v[76:77] op_sel_hi:[1,0]
	v_pk_mul_f32 v[48:49], v[54:55], v[76:77] op_sel_hi:[1,0]
	v_pk_mul_f32 v[52:53], v[64:65], v[76:77] op_sel_hi:[1,0]
	v_pk_mul_f32 v[54:55], v[62:63], v[76:77] op_sel_hi:[1,0]
	v_pk_mul_f32 v[56:57], v[60:61], v[76:77] op_sel_hi:[1,0]
	v_pk_fma_f32 v[0:1], v[4:5], v[48:49], v[0:1]
	v_pk_fma_f32 v[2:3], v[6:7], v[42:43], v[2:3]
	v_pk_fma_f32 v[4:5], v[66:67], v[44:45], v[70:71]
	v_pk_fma_f32 v[6:7], v[68:69], v[50:51], v[72:73]
	global_store_dwordx4 v[36:37], v[0:3], off offset:2048
	global_store_dwordx4 v[36:37], v[4:7], off offset:2064
	s_nop 1
	v_mov_b32_e32 v0, v198
	v_mov_b32_e32 v1, v199
	v_mov_b32_e32 v2, v200
	v_mov_b32_e32 v3, v201
	s_nop 0
	v_mov_b32_e32 v4, v166
	v_mov_b32_e32 v5, v167
	v_mov_b32_e32 v6, v168
	v_mov_b32_e32 v7, v169
	v_mov_b32_e32 v42, v170
	v_mov_b32_e32 v43, v171
	v_mov_b32_e32 v44, v172
	v_mov_b32_e32 v45, v173
	v_mov_b32_e32 v48, v202
	v_mov_b32_e32 v49, v203
	v_mov_b32_e32 v50, v204
	v_mov_b32_e32 v51, v205
	v_lshl_add_u64 v[36:37], v[74:75], 0, v[28:29]
	v_pk_fma_f32 v[0:1], v[4:5], v[40:41], v[0:1]
	v_pk_fma_f32 v[2:3], v[6:7], v[52:53], v[2:3]
	v_pk_fma_f32 v[4:5], v[42:43], v[56:57], v[48:49]
	v_pk_fma_f32 v[6:7], v[44:45], v[54:55], v[50:51]
	global_store_dwordx4 v[36:37], v[0:3], off
	global_store_dwordx4 v[36:37], v[4:7], off offset:16
	s_nop 1
	v_mov_b32_e32 v0, v206
	v_mov_b32_e32 v1, v207
	v_mov_b32_e32 v2, v208
	v_mov_b32_e32 v3, v209
	s_nop 0
	v_mov_b32_e32 v4, v174
	v_mov_b32_e32 v5, v175
	v_mov_b32_e32 v6, v176
	v_mov_b32_e32 v7, v177
	v_mov_b32_e32 v40, v178
	v_mov_b32_e32 v41, v179
	v_mov_b32_e32 v42, v180
	v_mov_b32_e32 v43, v181
	v_mov_b32_e32 v48, v210
	v_mov_b32_e32 v49, v211
	v_mov_b32_e32 v50, v212
	v_mov_b32_e32 v51, v213
	v_add_u32_e32 v36, s6, v34
	v_cmp_lt_i32_e32 vcc, s4, v36
	s_or_b64 s[0:1], vcc, s[0:1]
	v_lshl_add_u64 v[34:35], v[74:75], 0, v[30:31]
	v_pk_mul_f32 v[44:45], v[46:47], v[76:77] op_sel_hi:[1,0]
	v_pk_fma_f32 v[0:1], v[4:5], v[8:9], v[0:1]
	v_pk_fma_f32 v[2:3], v[6:7], v[38:39], v[2:3]
	v_pk_fma_f32 v[4:5], v[40:41], v[10:11], v[48:49]
	v_pk_fma_f32 v[6:7], v[42:43], v[44:45], v[50:51]
	global_store_dwordx4 v[34:35], v[0:3], off
	global_store_dwordx4 v[34:35], v[4:7], off offset:16
	s_andn2_b64 exec, exec, s[0:1]
	s_cbranch_execnz .LBB0_807
